# stack: U/V group-start wait relaxed + 32-token groups for U and V in the two latent-only layers
# baseline (speedup 1.0000x reference)
.LBB0_2966:
	s_or_b64 exec, exec, s[0:1]
	s_mov_b64 s[0:1], 0
	v_readlane_b32 s12, v250, 0
	s_waitcnt lgkmcnt(0)
	s_barrier
	v_readlane_b32 s14, v250, 2
	v_readlane_b32 s13, v250, 1
	v_readlane_b32 s15, v250, 3
	s_add_u32 s0, s14, s0
	s_addc_u32 s1, s15, s1
	s_mov_b64 s[16:17], 0
	s_mov_b64 s[14:15], 0
	s_mov_b64 s[12:13], 0
	s_mov_b64 s[10:11], 0
	s_mov_b64 s[8:9], 0
	s_mov_b64 s[36:37], 0
	s_mov_b64 s[10:11], 0
	v_mov_b32_e32 v2, v0
	s_add_u32 s0, s0, 0x6000
	s_getreg_b32 s2, hwreg(HW_REG_XCC_ID, 0, 4)
	v_and_b32_e32 v3, 63, v2
	s_addc_u32 s1, s1, 0
	s_and_b32 s33, s2, 7
	v_mov_b32_e32 v190, 0
	v_cmp_eq_u32_e64 s[8:9], 0, v3
	s_and_saveexec_b64 s[18:19], s[8:9]
	s_cbranch_execz .LBB0_2970
	s_mov_b64 s[22:23], exec
	v_mbcnt_lo_u32_b32 v4, s22, 0
	v_mbcnt_hi_u32_b32 v4, s23, v4
	v_cmp_eq_u32_e32 vcc, 0, v4
	s_and_saveexec_b64 s[20:21], vcc
	s_cbranch_execz .LBB0_2969
	s_bcnt1_i32_b64 s22, s[22:23]
	s_lshl_b32 s24, s33, 8
	s_lshl_b32 s22, s22, 5
	v_mov_b32_e32 v5, s24
	v_mov_b32_e32 v6, s22
	global_atomic_add v5, v5, v6, s[0:1] sc0
.LBB0_2969:
	s_or_b64 exec, exec, s[20:21]
	s_waitcnt vmcnt(0)
	v_readfirstlane_b32 s20, v5
	s_nop 1
	v_lshl_add_u32 v190, v4, 5, s20
.LBB0_2970:
	s_or_b64 exec, exec, s[18:19]
	v_readlane_b32 s40, v250, 0
	v_readlane_b32 s42, v250, 2
	v_readlane_b32 s43, v250, 3
	s_add_u32 s16, s42, s16
	s_addc_u32 s17, s43, s17
	s_add_u32 s26, s16, 0x49d86000
	s_addc_u32 s27, s17, 0
	s_add_u32 s14, s42, s14
	s_addc_u32 s15, s43, s15
	s_add_u32 s28, s14, 0x4c186000
	s_addc_u32 s29, s15, 0
	s_add_u32 s12, s42, s12
	s_addc_u32 s13, s43, s13
	s_add_u32 s14, s42, s36
	s_addc_u32 s15, s43, s37
	s_add_u32 s10, s42, s10
	s_addc_u32 s11, s43, s11
	v_lshlrev_b32_e32 v3, 3, v3
	s_add_u32 s30, s10, 0x3ad06000
	v_and_b32_e32 v6, 7, v2
	v_and_b32_e32 v193, 31, v2
	v_and_b32_e32 v178, 0x1c0, v3
	v_mov_b32_e32 v179, 0
	v_and_b32_e32 v3, 56, v2
	v_lshlrev_b32_e32 v2, 2, v2
	s_addc_u32 s31, s11, 0
	v_lshl_add_u64 v[4:5], s[12:13], 0, v[178:179]
	s_mov_b64 s[10:11], 0x2ade6000
	v_lshlrev_b32_e32 v178, 2, v3
	v_and_b32_e32 v2, 0xe0, v2
	v_mov_b32_e32 v3, v179
	v_lshl_add_u64 v[180:181], v[4:5], 0, s[10:11]
	v_lshl_add_u64 v[4:5], s[14:15], 0, v[178:179]
	v_lshlrev_b32_e32 v178, 2, v6
	v_lshl_add_u64 v[2:3], s[36:37], 0, v[2:3]
	v_lshl_add_u64 v[2:3], v[2:3], 0, v[178:179]
	v_lshl_add_u64 v[4:5], v[4:5], 0, v[178:179]
	s_mov_b64 s[38:39], 0x40d86000
	v_lshl_add_u64 v[2:3], s[42:43], 0, v[2:3]
	v_lshlrev_b32_e32 v191, 4, v6
	v_lshlrev_b32_e32 v192, 3, v6
	v_lshl_add_u64 v[182:183], v[4:5], 0, s[38:39]
	s_mov_b32 s35, 0
	v_cmp_eq_u32_e64 s[10:11], 0, v6
	v_cmp_eq_u32_e64 s[12:13], 1, v6
	v_cmp_eq_u32_e64 s[14:15], 2, v6
	v_cmp_eq_u32_e64 s[16:17], 3, v6
	v_cmp_eq_u32_e64 s[18:19], 4, v6
	v_cmp_eq_u32_e64 s[20:21], 5, v6
	v_cmp_eq_u32_e64 s[22:23], 6, v6
	v_cmp_eq_u32_e64 s[24:25], 7, v6
	v_lshl_add_u64 v[184:185], v[2:3], 0, s[38:39]
	v_mov_b32_e32 v194, 32
	s_mov_b32 s48, 0x5040100
	s_mov_b32 s49, 0x7060302
	s_mov_b64 s[36:37], 0x200
	s_mov_b32 s52, 0
	v_readlane_b32 s41, v250, 1
	s_branch .LBB0_2973

.LBB0_2977:
	s_add_i32 s39, s38, s54
	s_add_i32 s41, s39, 2
	s_add_i32 s40, s39, 1
	s_add_i32 s43, s39, 3
	s_cmp_lt_u32 s54, 30
	s_cselect_b32 s42, s41, s39
	s_cselect_b32 s44, s43, s40
	s_ashr_i32 s43, s42, 31
	s_lshl_b64 s[42:43], s[42:43], 9
	s_ashr_i32 s41, s40, 31
	s_lshl_b64 s[56:57], s[40:41], 11
	v_lshl_add_u64 v[26:27], v[180:181], 0, s[42:43]
	global_load_dwordx4 v[162:165], v[26:27], off offset:48
	global_load_dwordx4 v[166:169], v[26:27], off offset:32
	global_load_dwordx4 v[170:173], v[26:27], off offset:16
	global_load_dwordx4 v[174:177], v[26:27], off
	v_lshl_add_u64 v[26:27], v[186:187], 0, s[56:57]
	global_load_dwordx4 v[154:157], v[26:27], off offset:16
	global_load_dwordx4 v[158:161], v[26:27], off
	s_waitcnt vmcnt(25)
	v_lshl_add_u32 v26, v114, 7, v196
	v_lshl_add_u32 v27, v115, 7, v196
	global_load_dwordx4 v[150:153], v26, s[30:31]
	global_load_dwordx4 v[146:149], v27, s[30:31]
	v_lshl_add_u32 v26, v116, 7, v196
	v_lshl_add_u32 v27, v117, 7, v196
	global_load_dwordx4 v[142:145], v26, s[30:31]
	global_load_dwordx4 v[138:141], v27, s[30:31]
	v_lshl_add_u32 v26, v106, 7, v196
	v_lshl_add_u32 v27, v107, 7, v196
	global_load_dwordx4 v[134:137], v26, s[30:31]
	global_load_dwordx4 v[130:133], v27, s[30:31]
	v_lshl_add_u32 v26, v108, 7, v196
	v_lshl_add_u32 v27, v109, 7, v196
	global_load_dwordx4 v[126:129], v26, s[30:31]
	global_load_dwordx4 v[110:113], v27, s[30:31]
	v_lshl_add_u32 v26, v94, 7, v196
	v_lshl_add_u32 v27, v95, 7, v196
	global_load_dwordx4 v[98:101], v26, s[30:31]
	global_load_dwordx4 v[78:81], v27, s[30:31]
	v_lshl_add_u32 v26, v96, 7, v196
	v_lshl_add_u32 v27, v97, 7, v196
	global_load_dwordx4 v[70:73], v26, s[30:31]
	global_load_dwordx4 v[62:65], v27, s[30:31]
	s_waitcnt vmcnt(36)
	v_lshl_add_u32 v26, v82, 7, v196
	v_lshl_add_u32 v27, v83, 7, v196
	global_load_dwordx4 v[54:57], v26, s[30:31]
	global_load_dwordx4 v[46:49], v27, s[30:31]
	v_lshl_add_u32 v26, v84, 7, v196
	v_lshl_add_u32 v27, v85, 7, v196
	global_load_dwordx4 v[34:37], v26, s[30:31]
	s_nop 0
	global_load_dwordx4 v[26:29], v27, s[30:31]
	s_add_i32 s53, s54, 1
	s_cmp_lt_u32 s53, 31
	s_cselect_b64 s[42:43], -1, 0
	s_ashr_i32 s45, s44, 31
	s_lshl_b64 s[44:45], s[44:45], 9
	s_cmp_lg_u64 s[42:43], 0
	s_addc_u32 s42, s39, 1
	s_ashr_i32 s43, s42, 31
	s_lshl_b64 s[42:43], s[42:43], 11
	s_add_u32 s40, s40, s34
	s_addc_u32 s41, s41, 0
	s_lshl_b64 s[40:41], s[40:41], 8
	s_add_i32 s39, s54, 2
	s_cmp_gt_u32 s54, 29
	s_waitcnt vmcnt(39)
	v_perm_b32 v82, v91, v90, s48
	v_perm_b32 v84, v93, v92, s48
	s_waitcnt vmcnt(35)
	v_dot8_i32_i4 v96, v86, v82, 0
	v_perm_b32 v83, v91, v90, s49
	v_perm_b32 v90, v123, v122, s48
	v_dot8c_i32_i4_e32 v96, v87, v84
	v_perm_b32 v85, v93, v92, s49
	v_perm_b32 v92, v125, v124, s48
	v_dot8c_i32_i4_e32 v96, v88, v90
	v_dot8c_i32_i4_e32 v96, v89, v92
	v_dot8_i32_i4 v94, v118, v82, 0
	v_dot8_i32_i4 v95, v102, v82, 0
	v_perm_b32 v91, v123, v122, s49
	v_dot8c_i32_i4_e32 v94, v119, v84
	v_dot8c_i32_i4_e32 v95, v103, v84
	v_lshlrev_b32_e32 v96, 4, v96
	v_dot8c_i32_i4_e32 v96, v86, v83
	v_dot8c_i32_i4_e32 v96, v87, v85
	s_waitcnt vmcnt(34)
	v_dot8_i32_i4 v87, v74, v82, 0
	v_dot8c_i32_i4_e32 v94, v120, v90
	v_dot8c_i32_i4_e32 v87, v75, v84
	v_dot8c_i32_i4_e32 v87, v76, v90
	v_dot8c_i32_i4_e32 v87, v77, v92
	v_dot8c_i32_i4_e32 v95, v104, v90
	v_dot8c_i32_i4_e32 v94, v121, v92
	v_dot8c_i32_i4_e32 v95, v105, v92
	v_lshlrev_b32_e32 v87, 4, v87
	v_dot8c_i32_i4_e32 v87, v74, v83
	v_dot8c_i32_i4_e32 v87, v75, v85
	s_waitcnt vmcnt(33)
	v_dot8_i32_i4 v75, v66, v82, 0
	v_lshlrev_b32_e32 v94, 4, v94
	v_dot8c_i32_i4_e32 v75, v67, v84
	v_dot8c_i32_i4_e32 v75, v68, v90
	v_dot8c_i32_i4_e32 v75, v69, v92
	v_lshlrev_b32_e32 v95, 4, v95
	v_dot8c_i32_i4_e32 v94, v118, v83
	v_dot8c_i32_i4_e32 v95, v102, v83
	v_lshlrev_b32_e32 v75, 4, v75
	v_dot8c_i32_i4_e32 v75, v66, v83
	v_dot8c_i32_i4_e32 v75, v67, v85
	s_waitcnt vmcnt(32)
	v_dot8_i32_i4 v67, v58, v82, 0
	v_dot8c_i32_i4_e32 v94, v119, v85
	v_dot8c_i32_i4_e32 v67, v59, v84
	v_dot8c_i32_i4_e32 v67, v60, v90
	v_dot8c_i32_i4_e32 v67, v61, v92
	v_dot8c_i32_i4_e32 v95, v103, v85
	v_perm_b32 v93, v125, v124, s49
	v_dot8c_i32_i4_e32 v94, v120, v91
	v_lshlrev_b32_e32 v67, 4, v67
	v_dot8c_i32_i4_e32 v67, v58, v83
	v_dot8c_i32_i4_e32 v67, v59, v85
	s_waitcnt vmcnt(31)
	v_dot8_i32_i4 v59, v50, v82, 0
	v_dot8c_i32_i4_e32 v95, v104, v91
	v_dot8c_i32_i4_e32 v59, v51, v84
	v_dot8c_i32_i4_e32 v59, v52, v90
	v_dot8c_i32_i4_e32 v59, v53, v92
	v_dot8c_i32_i4_e32 v94, v121, v93
	v_dot8c_i32_i4_e32 v95, v105, v93
	v_dot8c_i32_i4_e32 v96, v88, v91
	v_lshlrev_b32_e32 v59, 4, v59
	v_dot8c_i32_i4_e32 v59, v50, v83
	v_dot8c_i32_i4_e32 v59, v51, v85
	s_waitcnt vmcnt(30)
	v_dot8_i32_i4 v51, v42, v82, 0
	v_dot8c_i32_i4_e32 v87, v76, v91
	v_dot8c_i32_i4_e32 v51, v43, v84
	v_dot8c_i32_i4_e32 v51, v44, v90
	v_dot8c_i32_i4_e32 v51, v45, v92
	v_add_u32_dpp v94, v94, v94 quad_perm:[1,0,3,2] row_mask:0xf bank_mask:0xf bound_ctrl:1
	v_add_u32_dpp v95, v95, v95 quad_perm:[1,0,3,2] row_mask:0xf bank_mask:0xf bound_ctrl:1
	v_dot8c_i32_i4_e32 v96, v89, v93
	v_lshlrev_b32_e32 v51, 4, v51
	v_dot8c_i32_i4_e32 v51, v42, v83
	v_dot8c_i32_i4_e32 v51, v43, v85
	s_waitcnt vmcnt(29)
	v_dot8_i32_i4 v43, v38, v82, 0
	v_dot8c_i32_i4_e32 v87, v77, v93
	v_dot8c_i32_i4_e32 v43, v39, v84
	v_dot8c_i32_i4_e32 v43, v40, v90
	v_dot8c_i32_i4_e32 v43, v41, v92
	v_dot8c_i32_i4_e32 v75, v68, v91
	v_dot8c_i32_i4_e32 v67, v60, v91
	v_add_u32_dpp v94, v94, v94 quad_perm:[2,3,0,1] row_mask:0xf bank_mask:0xf bound_ctrl:1
	v_lshlrev_b32_e32 v43, 4, v43
	v_dot8c_i32_i4_e32 v43, v38, v83
	v_dot8c_i32_i4_e32 v43, v39, v85
	s_waitcnt vmcnt(28)
	v_dot8_i32_i4 v39, v30, v82, 0
	v_add_u32_dpp v95, v95, v95 quad_perm:[2,3,0,1] row_mask:0xf bank_mask:0xf bound_ctrl:1
	v_dot8c_i32_i4_e32 v39, v31, v84
	v_dot8c_i32_i4_e32 v39, v32, v90
	v_dot8c_i32_i4_e32 v39, v33, v92
	v_add_u32_dpp v86, v96, v96 quad_perm:[1,0,3,2] row_mask:0xf bank_mask:0xf bound_ctrl:1
	v_add_u32_dpp v74, v87, v87 quad_perm:[1,0,3,2] row_mask:0xf bank_mask:0xf bound_ctrl:1
	v_dot8c_i32_i4_e32 v75, v69, v93
	v_lshlrev_b32_e32 v39, 4, v39
	v_dot8c_i32_i4_e32 v39, v30, v83
	v_dot8c_i32_i4_e32 v39, v31, v85
	s_waitcnt vmcnt(27)
	v_dot8_i32_i4 v31, v22, v82, 0
	v_dot8c_i32_i4_e32 v67, v61, v93
	v_dot8c_i32_i4_e32 v31, v23, v84
	v_dot8c_i32_i4_e32 v31, v24, v90
	v_dot8c_i32_i4_e32 v31, v25, v92
	v_dot8c_i32_i4_e32 v59, v52, v91
	v_dot8c_i32_i4_e32 v51, v44, v91
	v_add_u32_dpp v94, v94, v94 row_half_mirror row_mask:0xf bank_mask:0xf bound_ctrl:1
	v_lshlrev_b32_e32 v31, 4, v31
	v_dot8c_i32_i4_e32 v31, v22, v83
	v_dot8c_i32_i4_e32 v31, v23, v85
	s_waitcnt vmcnt(26)
	v_dot8_i32_i4 v23, v18, v82, 0
	v_add_u32_dpp v95, v95, v95 row_half_mirror row_mask:0xf bank_mask:0xf bound_ctrl:1
	v_dot8c_i32_i4_e32 v23, v19, v84
	v_dot8c_i32_i4_e32 v23, v20, v90
	v_dot8c_i32_i4_e32 v23, v21, v92
	v_add_u32_dpp v86, v86, v86 quad_perm:[2,3,0,1] row_mask:0xf bank_mask:0xf bound_ctrl:1
	v_add_u32_dpp v74, v74, v74 quad_perm:[2,3,0,1] row_mask:0xf bank_mask:0xf bound_ctrl:1
	v_add_u32_dpp v66, v75, v75 quad_perm:[1,0,3,2] row_mask:0xf bank_mask:0xf bound_ctrl:1
	v_lshlrev_b32_e32 v23, 4, v23
	v_dot8c_i32_i4_e32 v23, v18, v83
	v_dot8c_i32_i4_e32 v23, v19, v85
	s_waitcnt vmcnt(25)
	v_dot8_i32_i4 v19, v14, v82, 0
	v_add_u32_dpp v58, v67, v67 quad_perm:[1,0,3,2] row_mask:0xf bank_mask:0xf bound_ctrl:1
	v_dot8c_i32_i4_e32 v19, v15, v84
	v_dot8c_i32_i4_e32 v19, v16, v90
	v_dot8c_i32_i4_e32 v19, v17, v92
	v_dot8c_i32_i4_e32 v59, v53, v93
	v_dot8c_i32_i4_e32 v51, v45, v93
	v_dot8c_i32_i4_e32 v43, v40, v91
	v_lshlrev_b32_e32 v19, 4, v19
	v_dot8c_i32_i4_e32 v19, v14, v83
	v_dot8c_i32_i4_e32 v19, v15, v85
	s_waitcnt vmcnt(24)
	v_dot8_i32_i4 v15, v10, v82, 0
	v_dot8c_i32_i4_e32 v39, v32, v91
	v_dot8c_i32_i4_e32 v15, v11, v84
	v_dot8c_i32_i4_e32 v15, v12, v90
	v_dot8c_i32_i4_e32 v15, v13, v92
	v_cndmask_b32_e64 v94, 0, v94, s[10:11]
	v_cndmask_b32_e64 v95, 0, v95, s[10:11]
	v_add_u32_dpp v86, v86, v86 row_half_mirror row_mask:0xf bank_mask:0xf bound_ctrl:1
	v_lshlrev_b32_e32 v15, 4, v15
	v_dot8c_i32_i4_e32 v15, v10, v83
	v_dot8c_i32_i4_e32 v15, v11, v85
	s_waitcnt vmcnt(23)
	v_dot8_i32_i4 v11, v6, v82, 0
	v_add_u32_dpp v74, v74, v74 row_half_mirror row_mask:0xf bank_mask:0xf bound_ctrl:1
	v_dot8c_i32_i4_e32 v11, v7, v84
	v_dot8c_i32_i4_e32 v11, v8, v90
	v_dot8c_i32_i4_e32 v11, v9, v92
	v_add_u32_dpp v66, v66, v66 quad_perm:[2,3,0,1] row_mask:0xf bank_mask:0xf bound_ctrl:1
	v_add_u32_dpp v58, v58, v58 quad_perm:[2,3,0,1] row_mask:0xf bank_mask:0xf bound_ctrl:1
	v_add_u32_dpp v50, v59, v59 quad_perm:[1,0,3,2] row_mask:0xf bank_mask:0xf bound_ctrl:1
	v_lshlrev_b32_e32 v11, 4, v11
	v_dot8c_i32_i4_e32 v11, v6, v83
	v_dot8c_i32_i4_e32 v11, v7, v85
	s_waitcnt vmcnt(22)
	v_dot8_i32_i4 v7, v2, v82, 0
	v_add_u32_dpp v42, v51, v51 quad_perm:[1,0,3,2] row_mask:0xf bank_mask:0xf bound_ctrl:1
	v_dot8c_i32_i4_e32 v7, v3, v84
	v_dot8c_i32_i4_e32 v7, v4, v90
	v_dot8c_i32_i4_e32 v7, v5, v92
	v_dot8c_i32_i4_e32 v43, v41, v93
	v_dot8c_i32_i4_e32 v39, v33, v93
	v_dot8c_i32_i4_e32 v31, v24, v91
	v_lshlrev_b32_e32 v7, 4, v7
	v_dot8c_i32_i4_e32 v23, v20, v91
	v_dot8c_i32_i4_e32 v7, v2, v83
	v_cndmask_b32_e64 v86, v94, v86, s[12:13]
	v_cndmask_b32_e64 v74, v95, v74, s[12:13]
	v_add_u32_dpp v66, v66, v66 row_half_mirror row_mask:0xf bank_mask:0xf bound_ctrl:1
	v_add_u32_dpp v58, v58, v58 row_half_mirror row_mask:0xf bank_mask:0xf bound_ctrl:1
	v_add_u32_dpp v50, v50, v50 quad_perm:[2,3,0,1] row_mask:0xf bank_mask:0xf bound_ctrl:1
	v_add_u32_dpp v42, v42, v42 quad_perm:[2,3,0,1] row_mask:0xf bank_mask:0xf bound_ctrl:1
	v_add_u32_dpp v38, v43, v43 quad_perm:[1,0,3,2] row_mask:0xf bank_mask:0xf bound_ctrl:1
	v_add_u32_dpp v30, v39, v39 quad_perm:[1,0,3,2] row_mask:0xf bank_mask:0xf bound_ctrl:1
	v_dot8c_i32_i4_e32 v31, v25, v93
	v_dot8c_i32_i4_e32 v23, v21, v93
	v_dot8c_i32_i4_e32 v19, v16, v91
	v_dot8c_i32_i4_e32 v15, v12, v91
	v_dot8c_i32_i4_e32 v7, v3, v85
	v_cndmask_b32_e64 v66, v86, v66, s[14:15]
	v_cndmask_b32_e64 v58, v74, v58, s[14:15]
	v_add_u32_dpp v50, v50, v50 row_half_mirror row_mask:0xf bank_mask:0xf bound_ctrl:1
	v_add_u32_dpp v42, v42, v42 row_half_mirror row_mask:0xf bank_mask:0xf bound_ctrl:1
	v_add_u32_dpp v38, v38, v38 quad_perm:[2,3,0,1] row_mask:0xf bank_mask:0xf bound_ctrl:1
	v_add_u32_dpp v30, v30, v30 quad_perm:[2,3,0,1] row_mask:0xf bank_mask:0xf bound_ctrl:1
	v_add_u32_dpp v22, v31, v31 quad_perm:[1,0,3,2] row_mask:0xf bank_mask:0xf bound_ctrl:1
	v_add_u32_dpp v18, v23, v23 quad_perm:[1,0,3,2] row_mask:0xf bank_mask:0xf bound_ctrl:1
	v_dot8c_i32_i4_e32 v19, v17, v93
	v_dot8c_i32_i4_e32 v15, v13, v93
	v_dot8c_i32_i4_e32 v11, v8, v91
	v_dot8c_i32_i4_e32 v7, v4, v91
	v_cndmask_b32_e64 v50, v66, v50, s[16:17]
	v_cndmask_b32_e64 v42, v58, v42, s[16:17]
	v_add_u32_dpp v38, v38, v38 row_half_mirror row_mask:0xf bank_mask:0xf bound_ctrl:1
	v_add_u32_dpp v30, v30, v30 row_half_mirror row_mask:0xf bank_mask:0xf bound_ctrl:1
	v_add_u32_dpp v22, v22, v22 quad_perm:[2,3,0,1] row_mask:0xf bank_mask:0xf bound_ctrl:1
	v_add_u32_dpp v18, v18, v18 quad_perm:[2,3,0,1] row_mask:0xf bank_mask:0xf bound_ctrl:1
	v_add_u32_dpp v14, v19, v19 quad_perm:[1,0,3,2] row_mask:0xf bank_mask:0xf bound_ctrl:1
	v_add_u32_dpp v10, v15, v15 quad_perm:[1,0,3,2] row_mask:0xf bank_mask:0xf bound_ctrl:1
	v_dot8c_i32_i4_e32 v11, v9, v93
	v_dot8c_i32_i4_e32 v7, v5, v93
	v_cndmask_b32_e64 v38, v50, v38, s[18:19]
	v_cndmask_b32_e64 v30, v42, v30, s[18:19]
	v_add_u32_dpp v22, v22, v22 row_half_mirror row_mask:0xf bank_mask:0xf bound_ctrl:1
	v_add_u32_dpp v18, v18, v18 row_half_mirror row_mask:0xf bank_mask:0xf bound_ctrl:1
	v_add_u32_dpp v14, v14, v14 quad_perm:[2,3,0,1] row_mask:0xf bank_mask:0xf bound_ctrl:1
	v_add_u32_dpp v10, v10, v10 quad_perm:[2,3,0,1] row_mask:0xf bank_mask:0xf bound_ctrl:1
	v_add_u32_dpp v6, v11, v11 quad_perm:[1,0,3,2] row_mask:0xf bank_mask:0xf bound_ctrl:1
	v_add_u32_dpp v2, v7, v7 quad_perm:[1,0,3,2] row_mask:0xf bank_mask:0xf bound_ctrl:1
	v_cndmask_b32_e64 v22, v38, v22, s[20:21]
	v_cndmask_b32_e64 v18, v30, v18, s[20:21]
	v_add_u32_dpp v14, v14, v14 row_half_mirror row_mask:0xf bank_mask:0xf bound_ctrl:1
	v_add_u32_dpp v10, v10, v10 row_half_mirror row_mask:0xf bank_mask:0xf bound_ctrl:1
	v_add_u32_dpp v6, v6, v6 quad_perm:[2,3,0,1] row_mask:0xf bank_mask:0xf bound_ctrl:1
	v_add_u32_dpp v2, v2, v2 quad_perm:[2,3,0,1] row_mask:0xf bank_mask:0xf bound_ctrl:1
	v_cndmask_b32_e64 v14, v22, v14, s[22:23]
	v_cndmask_b32_e64 v10, v18, v10, s[22:23]
	v_add_u32_dpp v6, v6, v6 row_half_mirror row_mask:0xf bank_mask:0xf bound_ctrl:1
	v_add_u32_dpp v2, v2, v2 row_half_mirror row_mask:0xf bank_mask:0xf bound_ctrl:1
	v_cndmask_b32_e64 v6, v14, v6, s[24:25]
	v_cndmask_b32_e64 v2, v10, v2, s[24:25]
	v_cvt_f32_i32_e32 v3, v6
	v_cvt_f32_i32_e32 v2, v2
	v_readlane_b32 s54, v195, s54
	s_nop 1
	v_mul_f32_e32 v3, s54, v3
	v_mul_f32_e32 v2, s54, v2
	v_cvt_pk_f16_f32 v2, v3, v2
	global_store_dword v[188:189], v2, off
	v_lshl_add_u64 v[2:3], v[180:181], 0, s[44:45]
	global_load_dwordx4 v[82:85], v[2:3], off offset:48
	global_load_dwordx4 v[94:97], v[2:3], off offset:32
	global_load_dwordx4 v[106:109], v[2:3], off offset:16
	global_load_dwordx4 v[114:117], v[2:3], off
	v_lshl_add_u64 v[2:3], v[186:187], 0, s[42:43]
	global_load_dwordx4 v[122:125], v[2:3], off offset:16
	global_load_dwordx4 v[90:93], v[2:3], off
	s_waitcnt vmcnt(25)
	v_lshl_add_u32 v2, v174, 7, v196
	v_lshl_add_u32 v3, v175, 7, v196
	global_load_dwordx4 v[118:121], v2, s[30:31]
	global_load_dwordx4 v[102:105], v3, s[30:31]
	v_lshl_add_u32 v2, v176, 7, v196
	v_lshl_add_u32 v3, v177, 7, v196
	global_load_dwordx4 v[86:89], v2, s[30:31]
	global_load_dwordx4 v[74:77], v3, s[30:31]
	v_lshl_add_u32 v2, v170, 7, v196
	v_lshl_add_u32 v3, v171, 7, v196
	global_load_dwordx4 v[66:69], v2, s[30:31]
	global_load_dwordx4 v[58:61], v3, s[30:31]
	v_lshl_add_u32 v2, v172, 7, v196
	v_lshl_add_u32 v3, v173, 7, v196
	global_load_dwordx4 v[50:53], v2, s[30:31]
	global_load_dwordx4 v[42:45], v3, s[30:31]
	v_lshl_add_u32 v2, v166, 7, v196
	v_lshl_add_u32 v3, v167, 7, v196
	global_load_dwordx4 v[38:41], v2, s[30:31]
	global_load_dwordx4 v[30:33], v3, s[30:31]
	v_lshl_add_u32 v2, v168, 7, v196
	v_lshl_add_u32 v3, v169, 7, v196
	global_load_dwordx4 v[22:25], v2, s[30:31]
	global_load_dwordx4 v[18:21], v3, s[30:31]
	v_lshl_add_u32 v2, v162, 7, v196
	v_lshl_add_u32 v3, v163, 7, v196
	global_load_dwordx4 v[14:17], v2, s[30:31]
	global_load_dwordx4 v[10:13], v3, s[30:31]
	v_lshl_add_u32 v2, v164, 7, v196
	v_lshl_add_u32 v3, v165, 7, v196
	global_load_dwordx4 v[6:9], v2, s[30:31]
	s_nop 0
	global_load_dwordx4 v[2:5], v3, s[30:31]
	s_waitcnt vmcnt(39)
	v_perm_b32 v162, v159, v158, s48
	v_perm_b32 v158, v159, v158, s49
	v_perm_b32 v159, v161, v160, s48
	v_perm_b32 v160, v161, v160, s49
	v_perm_b32 v161, v155, v154, s48
	v_perm_b32 v154, v155, v154, s49
	v_perm_b32 v155, v157, v156, s48
	v_perm_b32 v156, v157, v156, s49
	s_waitcnt vmcnt(38)
	v_dot8_i32_i4 v157, v150, v162, 0
	v_readlane_b32 s42, v195, s53
	v_dot8c_i32_i4_e32 v157, v151, v159
	v_dot8c_i32_i4_e32 v157, v152, v161
	v_dot8c_i32_i4_e32 v157, v153, v155
	s_nop 2
	v_lshlrev_b32_e32 v157, 4, v157
	v_dot8c_i32_i4_e32 v157, v150, v158
	v_dot8c_i32_i4_e32 v157, v151, v160
	s_waitcnt vmcnt(37)
	v_dot8_i32_i4 v151, v146, v162, 0
	v_dot8c_i32_i4_e32 v157, v152, v154
	v_dot8c_i32_i4_e32 v151, v147, v159
	v_dot8c_i32_i4_e32 v151, v148, v161
	v_dot8c_i32_i4_e32 v151, v149, v155
	v_dot8c_i32_i4_e32 v157, v153, v156
	s_nop 1
	v_lshlrev_b32_e32 v151, 4, v151
	v_dot8c_i32_i4_e32 v151, v146, v158
	v_dot8c_i32_i4_e32 v151, v147, v160
	s_waitcnt vmcnt(36)
	v_dot8_i32_i4 v147, v142, v162, 0
	v_dot8c_i32_i4_e32 v151, v148, v154
	v_dot8c_i32_i4_e32 v147, v143, v159
	v_dot8c_i32_i4_e32 v147, v144, v161
	v_dot8c_i32_i4_e32 v147, v145, v155
	v_dot8c_i32_i4_e32 v151, v149, v156
	v_add_u32_dpp v150, v157, v157 quad_perm:[1,0,3,2] row_mask:0xf bank_mask:0xf bound_ctrl:1
	s_nop 0
	v_lshlrev_b32_e32 v147, 4, v147
	v_dot8c_i32_i4_e32 v147, v142, v158
	v_dot8c_i32_i4_e32 v147, v143, v160
	s_waitcnt vmcnt(35)
	v_dot8_i32_i4 v143, v138, v162, 0
	v_dot8c_i32_i4_e32 v147, v144, v154
	v_dot8c_i32_i4_e32 v143, v139, v159
	v_dot8c_i32_i4_e32 v143, v140, v161
	v_dot8c_i32_i4_e32 v143, v141, v155
	v_add_u32_dpp v146, v151, v151 quad_perm:[1,0,3,2] row_mask:0xf bank_mask:0xf bound_ctrl:1
	v_dot8c_i32_i4_e32 v147, v145, v156
	v_add_u32_dpp v150, v150, v150 quad_perm:[2,3,0,1] row_mask:0xf bank_mask:0xf bound_ctrl:1
	v_lshlrev_b32_e32 v143, 4, v143
	v_dot8c_i32_i4_e32 v143, v138, v158
	v_dot8c_i32_i4_e32 v143, v139, v160
	s_waitcnt vmcnt(34)
	v_dot8_i32_i4 v139, v134, v162, 0
	v_dot8c_i32_i4_e32 v143, v140, v154
	v_dot8c_i32_i4_e32 v139, v135, v159
	v_dot8c_i32_i4_e32 v139, v136, v161
	v_dot8c_i32_i4_e32 v139, v137, v155
	v_dot8c_i32_i4_e32 v143, v141, v156
	v_add_u32_dpp v146, v146, v146 quad_perm:[2,3,0,1] row_mask:0xf bank_mask:0xf bound_ctrl:1
	v_add_u32_dpp v142, v147, v147 quad_perm:[1,0,3,2] row_mask:0xf bank_mask:0xf bound_ctrl:1
	v_lshlrev_b32_e32 v139, 4, v139
	v_dot8c_i32_i4_e32 v139, v134, v158
	v_dot8c_i32_i4_e32 v139, v135, v160
	s_waitcnt vmcnt(33)
	v_dot8_i32_i4 v135, v130, v162, 0
	v_dot8c_i32_i4_e32 v139, v136, v154
	v_dot8c_i32_i4_e32 v135, v131, v159
	v_dot8c_i32_i4_e32 v135, v132, v161
	v_dot8c_i32_i4_e32 v135, v133, v155
	v_add_u32_dpp v138, v143, v143 quad_perm:[1,0,3,2] row_mask:0xf bank_mask:0xf bound_ctrl:1
	v_dot8c_i32_i4_e32 v139, v137, v156
	v_add_u32_dpp v150, v150, v150 row_half_mirror row_mask:0xf bank_mask:0xf bound_ctrl:1
	v_lshlrev_b32_e32 v135, 4, v135
	v_dot8c_i32_i4_e32 v135, v130, v158
	v_dot8c_i32_i4_e32 v135, v131, v160
	s_waitcnt vmcnt(32)
	v_dot8_i32_i4 v131, v126, v162, 0
	v_dot8c_i32_i4_e32 v135, v132, v154
	v_dot8c_i32_i4_e32 v131, v127, v159
	v_dot8c_i32_i4_e32 v131, v128, v161
	v_dot8c_i32_i4_e32 v131, v129, v155
	v_dot8c_i32_i4_e32 v135, v133, v156
	v_add_u32_dpp v146, v146, v146 row_half_mirror row_mask:0xf bank_mask:0xf bound_ctrl:1
	v_add_u32_dpp v142, v142, v142 quad_perm:[2,3,0,1] row_mask:0xf bank_mask:0xf bound_ctrl:1
	v_lshlrev_b32_e32 v131, 4, v131
	v_dot8c_i32_i4_e32 v131, v126, v158
	v_dot8c_i32_i4_e32 v131, v127, v160
	s_waitcnt vmcnt(31)
	v_dot8_i32_i4 v127, v110, v162, 0
	v_dot8c_i32_i4_e32 v131, v128, v154
	v_dot8c_i32_i4_e32 v127, v111, v159
	v_dot8c_i32_i4_e32 v127, v112, v161
	v_dot8c_i32_i4_e32 v127, v113, v155
	v_add_u32_dpp v138, v138, v138 quad_perm:[2,3,0,1] row_mask:0xf bank_mask:0xf bound_ctrl:1
	v_add_u32_dpp v134, v139, v139 quad_perm:[1,0,3,2] row_mask:0xf bank_mask:0xf bound_ctrl:1
	v_add_u32_dpp v130, v135, v135 quad_perm:[1,0,3,2] row_mask:0xf bank_mask:0xf bound_ctrl:1
	v_lshlrev_b32_e32 v127, 4, v127
	v_dot8c_i32_i4_e32 v127, v110, v158
	v_dot8c_i32_i4_e32 v127, v111, v160
	s_waitcnt vmcnt(30)
	v_dot8_i32_i4 v111, v98, v162, 0
	v_dot8c_i32_i4_e32 v127, v112, v154
	v_dot8c_i32_i4_e32 v111, v99, v159
	v_dot8c_i32_i4_e32 v111, v100, v161
	v_dot8c_i32_i4_e32 v111, v101, v155
	v_dot8c_i32_i4_e32 v131, v129, v156
	v_dot8c_i32_i4_e32 v127, v113, v156
	v_cndmask_b32_e64 v150, 0, v150, s[10:11]
	v_lshlrev_b32_e32 v111, 4, v111
	v_dot8c_i32_i4_e32 v111, v98, v158
	v_dot8c_i32_i4_e32 v111, v99, v160
	s_waitcnt vmcnt(29)
	v_dot8_i32_i4 v99, v78, v162, 0
	v_dot8c_i32_i4_e32 v111, v100, v154
	v_dot8c_i32_i4_e32 v99, v79, v159
	v_dot8c_i32_i4_e32 v99, v80, v161
	v_dot8c_i32_i4_e32 v99, v81, v155
	v_cndmask_b32_e64 v146, 0, v146, s[10:11]
	v_add_u32_dpp v142, v142, v142 row_half_mirror row_mask:0xf bank_mask:0xf bound_ctrl:1
	v_add_u32_dpp v138, v138, v138 row_half_mirror row_mask:0xf bank_mask:0xf bound_ctrl:1
	v_lshlrev_b32_e32 v99, 4, v99
	v_dot8c_i32_i4_e32 v99, v78, v158
	v_dot8c_i32_i4_e32 v99, v79, v160
	s_waitcnt vmcnt(28)
	v_dot8_i32_i4 v79, v70, v162, 0
	v_dot8c_i32_i4_e32 v99, v80, v154
	v_dot8c_i32_i4_e32 v79, v71, v159
	v_dot8c_i32_i4_e32 v79, v72, v161
	v_dot8c_i32_i4_e32 v79, v73, v155
	v_add_u32_dpp v134, v134, v134 quad_perm:[2,3,0,1] row_mask:0xf bank_mask:0xf bound_ctrl:1
	v_add_u32_dpp v130, v130, v130 quad_perm:[2,3,0,1] row_mask:0xf bank_mask:0xf bound_ctrl:1
	v_add_u32_dpp v126, v131, v131 quad_perm:[1,0,3,2] row_mask:0xf bank_mask:0xf bound_ctrl:1
	v_lshlrev_b32_e32 v79, 4, v79
	v_dot8c_i32_i4_e32 v79, v70, v158
	v_dot8c_i32_i4_e32 v79, v71, v160
	s_waitcnt vmcnt(27)
	v_dot8_i32_i4 v71, v62, v162, 0
	v_add_u32_dpp v110, v127, v127 quad_perm:[1,0,3,2] row_mask:0xf bank_mask:0xf bound_ctrl:1
	v_dot8c_i32_i4_e32 v71, v63, v159
	v_dot8c_i32_i4_e32 v71, v64, v161
	v_dot8c_i32_i4_e32 v71, v65, v155
	v_dot8c_i32_i4_e32 v111, v101, v156
	v_dot8c_i32_i4_e32 v99, v81, v156
	v_dot8c_i32_i4_e32 v79, v72, v154
	v_lshlrev_b32_e32 v71, 4, v71
	v_dot8c_i32_i4_e32 v71, v62, v158
	v_dot8c_i32_i4_e32 v71, v63, v160
	s_waitcnt vmcnt(26)
	v_dot8_i32_i4 v63, v54, v162, 0
	v_dot8c_i32_i4_e32 v71, v64, v154
	v_dot8c_i32_i4_e32 v63, v55, v159
	v_dot8c_i32_i4_e32 v63, v56, v161
	v_dot8c_i32_i4_e32 v63, v57, v155
	v_cndmask_b32_e64 v142, v150, v142, s[12:13]
	v_cndmask_b32_e64 v138, v146, v138, s[12:13]
	v_add_u32_dpp v134, v134, v134 row_half_mirror row_mask:0xf bank_mask:0xf bound_ctrl:1
	v_lshlrev_b32_e32 v63, 4, v63
	v_dot8c_i32_i4_e32 v63, v54, v158
	v_dot8c_i32_i4_e32 v63, v55, v160
	s_waitcnt vmcnt(25)
	v_dot8_i32_i4 v55, v46, v162, 0
	v_add_u32_dpp v130, v130, v130 row_half_mirror row_mask:0xf bank_mask:0xf bound_ctrl:1
	v_dot8c_i32_i4_e32 v55, v47, v159
	v_dot8c_i32_i4_e32 v55, v48, v161
	v_dot8c_i32_i4_e32 v55, v49, v155
	v_add_u32_dpp v126, v126, v126 quad_perm:[2,3,0,1] row_mask:0xf bank_mask:0xf bound_ctrl:1
	v_add_u32_dpp v110, v110, v110 quad_perm:[2,3,0,1] row_mask:0xf bank_mask:0xf bound_ctrl:1
	v_add_u32_dpp v98, v111, v111 quad_perm:[1,0,3,2] row_mask:0xf bank_mask:0xf bound_ctrl:1
	v_lshlrev_b32_e32 v55, 4, v55
	v_dot8c_i32_i4_e32 v55, v46, v158
	v_dot8c_i32_i4_e32 v55, v47, v160
	s_waitcnt vmcnt(24)
	v_dot8_i32_i4 v47, v34, v162, 0
	v_add_u32_dpp v78, v99, v99 quad_perm:[1,0,3,2] row_mask:0xf bank_mask:0xf bound_ctrl:1
	v_dot8c_i32_i4_e32 v47, v35, v159
	v_dot8c_i32_i4_e32 v47, v36, v161
	v_dot8c_i32_i4_e32 v47, v37, v155
	v_dot8c_i32_i4_e32 v79, v73, v156
	v_dot8c_i32_i4_e32 v71, v65, v156
	v_dot8c_i32_i4_e32 v63, v56, v154
	v_lshlrev_b32_e32 v47, 4, v47
	v_dot8c_i32_i4_e32 v47, v34, v158
	v_dot8c_i32_i4_e32 v47, v35, v160
	s_waitcnt vmcnt(23)
	v_dot8_i32_i4 v35, v26, v162, 0
	v_dot8c_i32_i4_e32 v55, v48, v154
	v_dot8c_i32_i4_e32 v35, v27, v159
	v_dot8c_i32_i4_e32 v35, v28, v161
	v_dot8c_i32_i4_e32 v35, v29, v155
	v_cndmask_b32_e64 v134, v142, v134, s[14:15]
	v_cndmask_b32_e64 v130, v138, v130, s[14:15]
	v_add_u32_dpp v126, v126, v126 row_half_mirror row_mask:0xf bank_mask:0xf bound_ctrl:1
	v_lshlrev_b32_e32 v35, 4, v35
	v_dot8c_i32_i4_e32 v35, v26, v158
	v_dot8c_i32_i4_e32 v35, v27, v160
	v_add_u32_dpp v110, v110, v110 row_half_mirror row_mask:0xf bank_mask:0xf bound_ctrl:1
	v_add_u32_dpp v98, v98, v98 quad_perm:[2,3,0,1] row_mask:0xf bank_mask:0xf bound_ctrl:1
	v_add_u32_dpp v78, v78, v78 quad_perm:[2,3,0,1] row_mask:0xf bank_mask:0xf bound_ctrl:1
	v_add_u32_dpp v70, v79, v79 quad_perm:[1,0,3,2] row_mask:0xf bank_mask:0xf bound_ctrl:1
	v_add_u32_dpp v62, v71, v71 quad_perm:[1,0,3,2] row_mask:0xf bank_mask:0xf bound_ctrl:1
	v_dot8c_i32_i4_e32 v63, v57, v156
	v_dot8c_i32_i4_e32 v55, v49, v156
	v_dot8c_i32_i4_e32 v47, v36, v154
	v_dot8c_i32_i4_e32 v35, v28, v154
	v_cndmask_b32_e64 v126, v134, v126, s[16:17]
	v_cndmask_b32_e64 v110, v130, v110, s[16:17]
	v_add_u32_dpp v98, v98, v98 row_half_mirror row_mask:0xf bank_mask:0xf bound_ctrl:1
	v_add_u32_dpp v78, v78, v78 row_half_mirror row_mask:0xf bank_mask:0xf bound_ctrl:1
	v_add_u32_dpp v70, v70, v70 quad_perm:[2,3,0,1] row_mask:0xf bank_mask:0xf bound_ctrl:1
	v_add_u32_dpp v62, v62, v62 quad_perm:[2,3,0,1] row_mask:0xf bank_mask:0xf bound_ctrl:1
	v_add_u32_dpp v54, v63, v63 quad_perm:[1,0,3,2] row_mask:0xf bank_mask:0xf bound_ctrl:1
	v_add_u32_dpp v46, v55, v55 quad_perm:[1,0,3,2] row_mask:0xf bank_mask:0xf bound_ctrl:1
	v_dot8c_i32_i4_e32 v47, v37, v156
	v_dot8c_i32_i4_e32 v35, v29, v156
	v_cndmask_b32_e64 v98, v126, v98, s[18:19]
	v_cndmask_b32_e64 v78, v110, v78, s[18:19]
	v_add_u32_dpp v70, v70, v70 row_half_mirror row_mask:0xf bank_mask:0xf bound_ctrl:1
	v_add_u32_dpp v62, v62, v62 row_half_mirror row_mask:0xf bank_mask:0xf bound_ctrl:1
	v_add_u32_dpp v54, v54, v54 quad_perm:[2,3,0,1] row_mask:0xf bank_mask:0xf bound_ctrl:1
	v_add_u32_dpp v46, v46, v46 quad_perm:[2,3,0,1] row_mask:0xf bank_mask:0xf bound_ctrl:1
	v_add_u32_dpp v34, v47, v47 quad_perm:[1,0,3,2] row_mask:0xf bank_mask:0xf bound_ctrl:1
	v_add_u32_dpp v26, v35, v35 quad_perm:[1,0,3,2] row_mask:0xf bank_mask:0xf bound_ctrl:1
	v_cndmask_b32_e64 v70, v98, v70, s[20:21]
	v_cndmask_b32_e64 v62, v78, v62, s[20:21]
	v_add_u32_dpp v54, v54, v54 row_half_mirror row_mask:0xf bank_mask:0xf bound_ctrl:1
	v_add_u32_dpp v46, v46, v46 row_half_mirror row_mask:0xf bank_mask:0xf bound_ctrl:1
	v_add_u32_dpp v34, v34, v34 quad_perm:[2,3,0,1] row_mask:0xf bank_mask:0xf bound_ctrl:1
	v_add_u32_dpp v26, v26, v26 quad_perm:[2,3,0,1] row_mask:0xf bank_mask:0xf bound_ctrl:1
	v_cndmask_b32_e64 v54, v70, v54, s[22:23]
	v_cndmask_b32_e64 v46, v62, v46, s[22:23]
	v_add_u32_dpp v34, v34, v34 row_half_mirror row_mask:0xf bank_mask:0xf bound_ctrl:1
	v_add_u32_dpp v26, v26, v26 row_half_mirror row_mask:0xf bank_mask:0xf bound_ctrl:1
	v_cndmask_b32_e64 v34, v54, v34, s[24:25]
	v_cndmask_b32_e64 v26, v46, v26, s[24:25]
	v_cvt_f32_i32_e32 v27, v34
	v_cvt_f32_i32_e32 v26, v26
	v_mul_f32_e32 v27, s42, v27
	v_mul_f32_e32 v26, s42, v26
	v_cvt_pk_f16_f32 v28, v27, v26
	v_lshl_add_u64 v[26:27], v[182:183], 0, s[40:41]
	global_store_dword v[26:27], v28, off
	v_lshl_add_u64 v[188:189], v[188:189], 0, s[36:37]
	s_mov_b32 s54, s39
	s_cbranch_scc0 .LBB0_2977
	s_mov_b64 s[40:41], 0

.LBB0_3951:
	s_or_b64 exec, exec, s[0:1]
	s_mov_b64 s[0:1], 0
	s_waitcnt lgkmcnt(0)
	s_barrier
	s_mov_b64 s[10:11], 0
	s_mov_b64 s[8:9], 0
	s_mov_b64 s[6:7], 0
	s_mov_b64 s[4:5], 0
	s_add_u32 s0, s54, s0
	s_mov_b64 s[2:3], 0
	s_addc_u32 s1, s55, s1
	s_mov_b64 s[28:29], 0
	s_mov_b64 s[4:5], 0
	v_mov_b32_e32 v2, v0
	s_add_u32 s0, s0, 0x7000
	s_getreg_b32 s33, hwreg(HW_REG_XCC_ID, 0, 4)
	v_and_b32_e32 v3, 63, v2
	s_addc_u32 s1, s1, 0
	s_and_b32 s40, s33, 7
	v_mov_b32_e32 v190, 0
	v_cmp_eq_u32_e64 s[2:3], 0, v3
	s_and_saveexec_b64 s[12:13], s[2:3]
	s_cbranch_execz .LBB0_3955
	s_mov_b64 s[16:17], exec
	v_mbcnt_lo_u32_b32 v4, s16, 0
	v_mbcnt_hi_u32_b32 v4, s17, v4
	v_cmp_eq_u32_e32 vcc, 0, v4
	s_and_saveexec_b64 s[14:15], vcc
	s_cbranch_execz .LBB0_3954
	s_bcnt1_i32_b64 s16, s[16:17]
	s_lshl_b32 s18, s40, 8
	s_lshl_b32 s16, s16, 5
	v_mov_b32_e32 v5, s18
	v_mov_b32_e32 v6, s16
	global_atomic_add v5, v5, v6, s[0:1] sc0
.LBB0_3954:
	s_or_b64 exec, exec, s[14:15]
	s_waitcnt vmcnt(0)
	v_readfirstlane_b32 s14, v5
	s_nop 1
	v_lshl_add_u32 v190, v4, 5, s14
.LBB0_3955:
	s_or_b64 exec, exec, s[12:13]
	s_add_u32 s10, s54, s10
	s_addc_u32 s11, s55, s11
	s_add_u32 s20, s10, 0x49d86000
	s_addc_u32 s21, s11, 0
	s_add_u32 s8, s54, s8
	s_addc_u32 s9, s55, s9
	s_add_u32 s22, s8, 0x4c186000
	s_addc_u32 s23, s9, 0
	s_add_u32 s6, s54, s6
	s_addc_u32 s7, s55, s7
	s_add_u32 s8, s54, s28
	s_addc_u32 s9, s55, s29
	s_add_u32 s4, s54, s4
	s_addc_u32 s5, s55, s5
	v_lshlrev_b32_e32 v3, 3, v3
	s_add_u32 s24, s4, 0x3bd06000
	v_and_b32_e32 v6, 7, v2
	v_and_b32_e32 v193, 31, v2
	v_and_b32_e32 v178, 0x1c0, v3
	v_mov_b32_e32 v179, 0
	v_and_b32_e32 v3, 56, v2
	v_lshlrev_b32_e32 v2, 2, v2
	s_addc_u32 s25, s5, 0
	v_lshl_add_u64 v[4:5], s[6:7], 0, v[178:179]
	s_mov_b64 s[4:5], 0x2ade6000
	v_lshlrev_b32_e32 v178, 2, v3
	v_and_b32_e32 v2, 0xe0, v2
	v_mov_b32_e32 v3, v179
	v_lshl_add_u64 v[180:181], v[4:5], 0, s[4:5]
	v_lshl_add_u64 v[4:5], s[8:9], 0, v[178:179]
	v_lshlrev_b32_e32 v178, 2, v6
	v_lshl_add_u64 v[2:3], s[28:29], 0, v[2:3]
	v_lshl_add_u64 v[2:3], v[2:3], 0, v[178:179]
	v_lshl_add_u64 v[4:5], v[4:5], 0, v[178:179]
	s_mov_b64 s[30:31], 0x40d86000
	v_lshl_add_u64 v[2:3], s[54:55], 0, v[2:3]
	v_lshlrev_b32_e32 v191, 4, v6
	v_lshlrev_b32_e32 v192, 3, v6
	v_lshl_add_u64 v[182:183], v[4:5], 0, s[30:31]
	s_mov_b32 s27, 0
	v_cmp_eq_u32_e64 s[4:5], 0, v6
	v_cmp_eq_u32_e64 s[6:7], 1, v6
	v_cmp_eq_u32_e64 s[8:9], 2, v6
	v_cmp_eq_u32_e64 s[10:11], 3, v6
	v_cmp_eq_u32_e64 s[12:13], 4, v6
	v_cmp_eq_u32_e64 s[14:15], 5, v6
	v_cmp_eq_u32_e64 s[16:17], 6, v6
	v_cmp_eq_u32_e64 s[18:19], 7, v6
	v_lshl_add_u64 v[184:185], v[2:3], 0, s[30:31]
	v_mov_b32_e32 v194, 32
	s_mov_b32 s41, 0x5040100
	s_mov_b32 s42, 0x7060302
	s_mov_b64 s[28:29], 0x200
	s_mov_b32 s43, 0
	s_branch .LBB0_3958

.LBB0_3962:
	s_add_i32 s31, s30, s47
	s_add_i32 s35, s31, 2
	s_add_i32 s34, s31, 1
	s_add_i32 s37, s31, 3
	s_cmp_lt_u32 s47, 30
	s_cselect_b32 s36, s35, s31
	s_cselect_b32 s38, s37, s34
	s_ashr_i32 s37, s36, 31
	s_lshl_b64 s[36:37], s[36:37], 9
	s_ashr_i32 s35, s34, 31
	s_lshl_b64 s[48:49], s[34:35], 11
	v_lshl_add_u64 v[26:27], v[180:181], 0, s[36:37]
	global_load_dwordx4 v[162:165], v[26:27], off offset:48
	global_load_dwordx4 v[166:169], v[26:27], off offset:32
	global_load_dwordx4 v[170:173], v[26:27], off offset:16
	global_load_dwordx4 v[174:177], v[26:27], off
	v_lshl_add_u64 v[26:27], v[186:187], 0, s[48:49]
	global_load_dwordx4 v[154:157], v[26:27], off offset:16
	global_load_dwordx4 v[158:161], v[26:27], off
	s_waitcnt vmcnt(25)
	v_lshl_add_u32 v26, v114, 7, v196
	v_lshl_add_u32 v27, v115, 7, v196
	global_load_dwordx4 v[150:153], v26, s[24:25]
	global_load_dwordx4 v[146:149], v27, s[24:25]
	v_lshl_add_u32 v26, v116, 7, v196
	v_lshl_add_u32 v27, v117, 7, v196
	global_load_dwordx4 v[142:145], v26, s[24:25]
	global_load_dwordx4 v[138:141], v27, s[24:25]
	v_lshl_add_u32 v26, v106, 7, v196
	v_lshl_add_u32 v27, v107, 7, v196
	global_load_dwordx4 v[134:137], v26, s[24:25]
	global_load_dwordx4 v[130:133], v27, s[24:25]
	v_lshl_add_u32 v26, v108, 7, v196
	v_lshl_add_u32 v27, v109, 7, v196
	global_load_dwordx4 v[126:129], v26, s[24:25]
	global_load_dwordx4 v[110:113], v27, s[24:25]
	v_lshl_add_u32 v26, v94, 7, v196
	v_lshl_add_u32 v27, v95, 7, v196
	global_load_dwordx4 v[98:101], v26, s[24:25]
	global_load_dwordx4 v[78:81], v27, s[24:25]
	v_lshl_add_u32 v26, v96, 7, v196
	v_lshl_add_u32 v27, v97, 7, v196
	global_load_dwordx4 v[70:73], v26, s[24:25]
	global_load_dwordx4 v[62:65], v27, s[24:25]
	s_waitcnt vmcnt(36)
	v_lshl_add_u32 v26, v82, 7, v196
	v_lshl_add_u32 v27, v83, 7, v196
	global_load_dwordx4 v[54:57], v26, s[24:25]
	global_load_dwordx4 v[46:49], v27, s[24:25]
	v_lshl_add_u32 v26, v84, 7, v196
	v_lshl_add_u32 v27, v85, 7, v196
	global_load_dwordx4 v[34:37], v26, s[24:25]
	s_nop 0
	global_load_dwordx4 v[26:29], v27, s[24:25]
	s_add_i32 s46, s47, 1
	s_cmp_lt_u32 s46, 31
	s_cselect_b64 s[36:37], -1, 0
	s_ashr_i32 s39, s38, 31
	s_lshl_b64 s[38:39], s[38:39], 9
	s_cmp_lg_u64 s[36:37], 0
	s_addc_u32 s36, s31, 1
	s_ashr_i32 s37, s36, 31
	s_lshl_b64 s[36:37], s[36:37], 11
	s_add_u32 s34, s34, s26
	s_addc_u32 s35, s35, 0
	s_lshl_b64 s[34:35], s[34:35], 8
	s_add_i32 s31, s47, 2
	s_cmp_gt_u32 s47, 29
	s_waitcnt vmcnt(39)
	v_perm_b32 v82, v91, v90, s41
	v_perm_b32 v84, v93, v92, s41
	s_waitcnt vmcnt(35)
	v_dot8_i32_i4 v96, v86, v82, 0
	v_perm_b32 v83, v91, v90, s42
	v_perm_b32 v90, v123, v122, s41
	v_dot8c_i32_i4_e32 v96, v87, v84
	v_perm_b32 v85, v93, v92, s42
	v_perm_b32 v92, v125, v124, s41
	v_dot8c_i32_i4_e32 v96, v88, v90
	v_dot8c_i32_i4_e32 v96, v89, v92
	v_dot8_i32_i4 v94, v118, v82, 0
	v_dot8_i32_i4 v95, v102, v82, 0
	v_perm_b32 v91, v123, v122, s42
	v_dot8c_i32_i4_e32 v94, v119, v84
	v_dot8c_i32_i4_e32 v95, v103, v84
	v_lshlrev_b32_e32 v96, 4, v96
	v_dot8c_i32_i4_e32 v96, v86, v83
	v_dot8c_i32_i4_e32 v96, v87, v85
	s_waitcnt vmcnt(34)
	v_dot8_i32_i4 v87, v74, v82, 0
	v_dot8c_i32_i4_e32 v94, v120, v90
	v_dot8c_i32_i4_e32 v87, v75, v84
	v_dot8c_i32_i4_e32 v87, v76, v90
	v_dot8c_i32_i4_e32 v87, v77, v92
	v_dot8c_i32_i4_e32 v95, v104, v90
	v_dot8c_i32_i4_e32 v94, v121, v92
	v_dot8c_i32_i4_e32 v95, v105, v92
	v_lshlrev_b32_e32 v87, 4, v87
	v_dot8c_i32_i4_e32 v87, v74, v83
	v_dot8c_i32_i4_e32 v87, v75, v85
	s_waitcnt vmcnt(33)
	v_dot8_i32_i4 v75, v66, v82, 0
	v_lshlrev_b32_e32 v94, 4, v94
	v_dot8c_i32_i4_e32 v75, v67, v84
	v_dot8c_i32_i4_e32 v75, v68, v90
	v_dot8c_i32_i4_e32 v75, v69, v92
	v_lshlrev_b32_e32 v95, 4, v95
	v_dot8c_i32_i4_e32 v94, v118, v83
	v_dot8c_i32_i4_e32 v95, v102, v83
	v_lshlrev_b32_e32 v75, 4, v75
	v_dot8c_i32_i4_e32 v75, v66, v83
	v_dot8c_i32_i4_e32 v75, v67, v85
	s_waitcnt vmcnt(32)
	v_dot8_i32_i4 v67, v58, v82, 0
	v_dot8c_i32_i4_e32 v94, v119, v85
	v_dot8c_i32_i4_e32 v67, v59, v84
	v_dot8c_i32_i4_e32 v67, v60, v90
	v_dot8c_i32_i4_e32 v67, v61, v92
	v_dot8c_i32_i4_e32 v95, v103, v85
	v_perm_b32 v93, v125, v124, s42
	v_dot8c_i32_i4_e32 v94, v120, v91
	v_lshlrev_b32_e32 v67, 4, v67
	v_dot8c_i32_i4_e32 v67, v58, v83
	v_dot8c_i32_i4_e32 v67, v59, v85
	s_waitcnt vmcnt(31)
	v_dot8_i32_i4 v59, v50, v82, 0
	v_dot8c_i32_i4_e32 v95, v104, v91
	v_dot8c_i32_i4_e32 v59, v51, v84
	v_dot8c_i32_i4_e32 v59, v52, v90
	v_dot8c_i32_i4_e32 v59, v53, v92
	v_dot8c_i32_i4_e32 v94, v121, v93
	v_dot8c_i32_i4_e32 v95, v105, v93
	v_dot8c_i32_i4_e32 v96, v88, v91
	v_lshlrev_b32_e32 v59, 4, v59
	v_dot8c_i32_i4_e32 v59, v50, v83
	v_dot8c_i32_i4_e32 v59, v51, v85
	s_waitcnt vmcnt(30)
	v_dot8_i32_i4 v51, v42, v82, 0
	v_dot8c_i32_i4_e32 v87, v76, v91
	v_dot8c_i32_i4_e32 v51, v43, v84
	v_dot8c_i32_i4_e32 v51, v44, v90
	v_dot8c_i32_i4_e32 v51, v45, v92
	v_add_u32_dpp v94, v94, v94 quad_perm:[1,0,3,2] row_mask:0xf bank_mask:0xf bound_ctrl:1
	v_add_u32_dpp v95, v95, v95 quad_perm:[1,0,3,2] row_mask:0xf bank_mask:0xf bound_ctrl:1
	v_dot8c_i32_i4_e32 v96, v89, v93
	v_lshlrev_b32_e32 v51, 4, v51
	v_dot8c_i32_i4_e32 v51, v42, v83
	v_dot8c_i32_i4_e32 v51, v43, v85
	s_waitcnt vmcnt(29)
	v_dot8_i32_i4 v43, v38, v82, 0
	v_dot8c_i32_i4_e32 v87, v77, v93
	v_dot8c_i32_i4_e32 v43, v39, v84
	v_dot8c_i32_i4_e32 v43, v40, v90
	v_dot8c_i32_i4_e32 v43, v41, v92
	v_dot8c_i32_i4_e32 v75, v68, v91
	v_dot8c_i32_i4_e32 v67, v60, v91
	v_add_u32_dpp v94, v94, v94 quad_perm:[2,3,0,1] row_mask:0xf bank_mask:0xf bound_ctrl:1
	v_lshlrev_b32_e32 v43, 4, v43
	v_dot8c_i32_i4_e32 v43, v38, v83
	v_dot8c_i32_i4_e32 v43, v39, v85
	s_waitcnt vmcnt(28)
	v_dot8_i32_i4 v39, v30, v82, 0
	v_add_u32_dpp v95, v95, v95 quad_perm:[2,3,0,1] row_mask:0xf bank_mask:0xf bound_ctrl:1
	v_dot8c_i32_i4_e32 v39, v31, v84
	v_dot8c_i32_i4_e32 v39, v32, v90
	v_dot8c_i32_i4_e32 v39, v33, v92
	v_add_u32_dpp v86, v96, v96 quad_perm:[1,0,3,2] row_mask:0xf bank_mask:0xf bound_ctrl:1
	v_add_u32_dpp v74, v87, v87 quad_perm:[1,0,3,2] row_mask:0xf bank_mask:0xf bound_ctrl:1
	v_dot8c_i32_i4_e32 v75, v69, v93
	v_lshlrev_b32_e32 v39, 4, v39
	v_dot8c_i32_i4_e32 v39, v30, v83
	v_dot8c_i32_i4_e32 v39, v31, v85
	s_waitcnt vmcnt(27)
	v_dot8_i32_i4 v31, v22, v82, 0
	v_dot8c_i32_i4_e32 v67, v61, v93
	v_dot8c_i32_i4_e32 v31, v23, v84
	v_dot8c_i32_i4_e32 v31, v24, v90
	v_dot8c_i32_i4_e32 v31, v25, v92
	v_dot8c_i32_i4_e32 v59, v52, v91
	v_dot8c_i32_i4_e32 v51, v44, v91
	v_add_u32_dpp v94, v94, v94 row_half_mirror row_mask:0xf bank_mask:0xf bound_ctrl:1
	v_lshlrev_b32_e32 v31, 4, v31
	v_dot8c_i32_i4_e32 v31, v22, v83
	v_dot8c_i32_i4_e32 v31, v23, v85
	s_waitcnt vmcnt(26)
	v_dot8_i32_i4 v23, v18, v82, 0
	v_add_u32_dpp v95, v95, v95 row_half_mirror row_mask:0xf bank_mask:0xf bound_ctrl:1
	v_dot8c_i32_i4_e32 v23, v19, v84
	v_dot8c_i32_i4_e32 v23, v20, v90
	v_dot8c_i32_i4_e32 v23, v21, v92
	v_add_u32_dpp v86, v86, v86 quad_perm:[2,3,0,1] row_mask:0xf bank_mask:0xf bound_ctrl:1
	v_add_u32_dpp v74, v74, v74 quad_perm:[2,3,0,1] row_mask:0xf bank_mask:0xf bound_ctrl:1
	v_add_u32_dpp v66, v75, v75 quad_perm:[1,0,3,2] row_mask:0xf bank_mask:0xf bound_ctrl:1
	v_lshlrev_b32_e32 v23, 4, v23
	v_dot8c_i32_i4_e32 v23, v18, v83
	v_dot8c_i32_i4_e32 v23, v19, v85
	s_waitcnt vmcnt(25)
	v_dot8_i32_i4 v19, v14, v82, 0
	v_add_u32_dpp v58, v67, v67 quad_perm:[1,0,3,2] row_mask:0xf bank_mask:0xf bound_ctrl:1
	v_dot8c_i32_i4_e32 v19, v15, v84
	v_dot8c_i32_i4_e32 v19, v16, v90
	v_dot8c_i32_i4_e32 v19, v17, v92
	v_dot8c_i32_i4_e32 v59, v53, v93
	v_dot8c_i32_i4_e32 v51, v45, v93
	v_dot8c_i32_i4_e32 v43, v40, v91
	v_lshlrev_b32_e32 v19, 4, v19
	v_dot8c_i32_i4_e32 v19, v14, v83
	v_dot8c_i32_i4_e32 v19, v15, v85
	s_waitcnt vmcnt(24)
	v_dot8_i32_i4 v15, v10, v82, 0
	v_dot8c_i32_i4_e32 v39, v32, v91
	v_dot8c_i32_i4_e32 v15, v11, v84
	v_dot8c_i32_i4_e32 v15, v12, v90
	v_dot8c_i32_i4_e32 v15, v13, v92
	v_cndmask_b32_e64 v94, 0, v94, s[4:5]
	v_cndmask_b32_e64 v95, 0, v95, s[4:5]
	v_add_u32_dpp v86, v86, v86 row_half_mirror row_mask:0xf bank_mask:0xf bound_ctrl:1
	v_lshlrev_b32_e32 v15, 4, v15
	v_dot8c_i32_i4_e32 v15, v10, v83
	v_dot8c_i32_i4_e32 v15, v11, v85
	s_waitcnt vmcnt(23)
	v_dot8_i32_i4 v11, v6, v82, 0
	v_add_u32_dpp v74, v74, v74 row_half_mirror row_mask:0xf bank_mask:0xf bound_ctrl:1
	v_dot8c_i32_i4_e32 v11, v7, v84
	v_dot8c_i32_i4_e32 v11, v8, v90
	v_dot8c_i32_i4_e32 v11, v9, v92
	v_add_u32_dpp v66, v66, v66 quad_perm:[2,3,0,1] row_mask:0xf bank_mask:0xf bound_ctrl:1
	v_add_u32_dpp v58, v58, v58 quad_perm:[2,3,0,1] row_mask:0xf bank_mask:0xf bound_ctrl:1
	v_add_u32_dpp v50, v59, v59 quad_perm:[1,0,3,2] row_mask:0xf bank_mask:0xf bound_ctrl:1
	v_lshlrev_b32_e32 v11, 4, v11
	v_dot8c_i32_i4_e32 v11, v6, v83
	v_dot8c_i32_i4_e32 v11, v7, v85
	s_waitcnt vmcnt(22)
	v_dot8_i32_i4 v7, v2, v82, 0
	v_add_u32_dpp v42, v51, v51 quad_perm:[1,0,3,2] row_mask:0xf bank_mask:0xf bound_ctrl:1
	v_dot8c_i32_i4_e32 v7, v3, v84
	v_dot8c_i32_i4_e32 v7, v4, v90
	v_dot8c_i32_i4_e32 v7, v5, v92
	v_dot8c_i32_i4_e32 v43, v41, v93
	v_dot8c_i32_i4_e32 v39, v33, v93
	v_dot8c_i32_i4_e32 v31, v24, v91
	v_lshlrev_b32_e32 v7, 4, v7
	v_dot8c_i32_i4_e32 v23, v20, v91
	v_dot8c_i32_i4_e32 v7, v2, v83
	v_cndmask_b32_e64 v86, v94, v86, s[6:7]
	v_cndmask_b32_e64 v74, v95, v74, s[6:7]
	v_add_u32_dpp v66, v66, v66 row_half_mirror row_mask:0xf bank_mask:0xf bound_ctrl:1
	v_add_u32_dpp v58, v58, v58 row_half_mirror row_mask:0xf bank_mask:0xf bound_ctrl:1
	v_add_u32_dpp v50, v50, v50 quad_perm:[2,3,0,1] row_mask:0xf bank_mask:0xf bound_ctrl:1
	v_add_u32_dpp v42, v42, v42 quad_perm:[2,3,0,1] row_mask:0xf bank_mask:0xf bound_ctrl:1
	v_add_u32_dpp v38, v43, v43 quad_perm:[1,0,3,2] row_mask:0xf bank_mask:0xf bound_ctrl:1
	v_add_u32_dpp v30, v39, v39 quad_perm:[1,0,3,2] row_mask:0xf bank_mask:0xf bound_ctrl:1
	v_dot8c_i32_i4_e32 v31, v25, v93
	v_dot8c_i32_i4_e32 v23, v21, v93
	v_dot8c_i32_i4_e32 v19, v16, v91
	v_dot8c_i32_i4_e32 v15, v12, v91
	v_dot8c_i32_i4_e32 v7, v3, v85
	v_cndmask_b32_e64 v66, v86, v66, s[8:9]
	v_cndmask_b32_e64 v58, v74, v58, s[8:9]
	v_add_u32_dpp v50, v50, v50 row_half_mirror row_mask:0xf bank_mask:0xf bound_ctrl:1
	v_add_u32_dpp v42, v42, v42 row_half_mirror row_mask:0xf bank_mask:0xf bound_ctrl:1
	v_add_u32_dpp v38, v38, v38 quad_perm:[2,3,0,1] row_mask:0xf bank_mask:0xf bound_ctrl:1
	v_add_u32_dpp v30, v30, v30 quad_perm:[2,3,0,1] row_mask:0xf bank_mask:0xf bound_ctrl:1
	v_add_u32_dpp v22, v31, v31 quad_perm:[1,0,3,2] row_mask:0xf bank_mask:0xf bound_ctrl:1
	v_add_u32_dpp v18, v23, v23 quad_perm:[1,0,3,2] row_mask:0xf bank_mask:0xf bound_ctrl:1
	v_dot8c_i32_i4_e32 v19, v17, v93
	v_dot8c_i32_i4_e32 v15, v13, v93
	v_dot8c_i32_i4_e32 v11, v8, v91
	v_dot8c_i32_i4_e32 v7, v4, v91
	v_cndmask_b32_e64 v50, v66, v50, s[10:11]
	v_cndmask_b32_e64 v42, v58, v42, s[10:11]
	v_add_u32_dpp v38, v38, v38 row_half_mirror row_mask:0xf bank_mask:0xf bound_ctrl:1
	v_add_u32_dpp v30, v30, v30 row_half_mirror row_mask:0xf bank_mask:0xf bound_ctrl:1
	v_add_u32_dpp v22, v22, v22 quad_perm:[2,3,0,1] row_mask:0xf bank_mask:0xf bound_ctrl:1
	v_add_u32_dpp v18, v18, v18 quad_perm:[2,3,0,1] row_mask:0xf bank_mask:0xf bound_ctrl:1
	v_add_u32_dpp v14, v19, v19 quad_perm:[1,0,3,2] row_mask:0xf bank_mask:0xf bound_ctrl:1
	v_add_u32_dpp v10, v15, v15 quad_perm:[1,0,3,2] row_mask:0xf bank_mask:0xf bound_ctrl:1
	v_dot8c_i32_i4_e32 v11, v9, v93
	v_dot8c_i32_i4_e32 v7, v5, v93
	v_cndmask_b32_e64 v38, v50, v38, s[12:13]
	v_cndmask_b32_e64 v30, v42, v30, s[12:13]
	v_add_u32_dpp v22, v22, v22 row_half_mirror row_mask:0xf bank_mask:0xf bound_ctrl:1
	v_add_u32_dpp v18, v18, v18 row_half_mirror row_mask:0xf bank_mask:0xf bound_ctrl:1
	v_add_u32_dpp v14, v14, v14 quad_perm:[2,3,0,1] row_mask:0xf bank_mask:0xf bound_ctrl:1
	v_add_u32_dpp v10, v10, v10 quad_perm:[2,3,0,1] row_mask:0xf bank_mask:0xf bound_ctrl:1
	v_add_u32_dpp v6, v11, v11 quad_perm:[1,0,3,2] row_mask:0xf bank_mask:0xf bound_ctrl:1
	v_add_u32_dpp v2, v7, v7 quad_perm:[1,0,3,2] row_mask:0xf bank_mask:0xf bound_ctrl:1
	v_cndmask_b32_e64 v22, v38, v22, s[14:15]
	v_cndmask_b32_e64 v18, v30, v18, s[14:15]
	v_add_u32_dpp v14, v14, v14 row_half_mirror row_mask:0xf bank_mask:0xf bound_ctrl:1
	v_add_u32_dpp v10, v10, v10 row_half_mirror row_mask:0xf bank_mask:0xf bound_ctrl:1
	v_add_u32_dpp v6, v6, v6 quad_perm:[2,3,0,1] row_mask:0xf bank_mask:0xf bound_ctrl:1
	v_add_u32_dpp v2, v2, v2 quad_perm:[2,3,0,1] row_mask:0xf bank_mask:0xf bound_ctrl:1
	v_cndmask_b32_e64 v14, v22, v14, s[16:17]
	v_cndmask_b32_e64 v10, v18, v10, s[16:17]
	v_add_u32_dpp v6, v6, v6 row_half_mirror row_mask:0xf bank_mask:0xf bound_ctrl:1
	v_add_u32_dpp v2, v2, v2 row_half_mirror row_mask:0xf bank_mask:0xf bound_ctrl:1
	v_cndmask_b32_e64 v6, v14, v6, s[18:19]
	v_cndmask_b32_e64 v2, v10, v2, s[18:19]
	v_cvt_f32_i32_e32 v3, v6
	v_cvt_f32_i32_e32 v2, v2
	v_readlane_b32 s47, v195, s47
	s_nop 1
	v_mul_f32_e32 v3, s47, v3
	v_mul_f32_e32 v2, s47, v2
	v_cvt_pk_f16_f32 v2, v3, v2
	global_store_dword v[188:189], v2, off
	v_lshl_add_u64 v[2:3], v[180:181], 0, s[38:39]
	global_load_dwordx4 v[82:85], v[2:3], off offset:48
	global_load_dwordx4 v[94:97], v[2:3], off offset:32
	global_load_dwordx4 v[106:109], v[2:3], off offset:16
	global_load_dwordx4 v[114:117], v[2:3], off
	v_lshl_add_u64 v[2:3], v[186:187], 0, s[36:37]
	global_load_dwordx4 v[122:125], v[2:3], off offset:16
	global_load_dwordx4 v[90:93], v[2:3], off
	s_waitcnt vmcnt(25)
	v_lshl_add_u32 v2, v174, 7, v196
	v_lshl_add_u32 v3, v175, 7, v196
	global_load_dwordx4 v[118:121], v2, s[24:25]
	global_load_dwordx4 v[102:105], v3, s[24:25]
	v_lshl_add_u32 v2, v176, 7, v196
	v_lshl_add_u32 v3, v177, 7, v196
	global_load_dwordx4 v[86:89], v2, s[24:25]
	global_load_dwordx4 v[74:77], v3, s[24:25]
	v_lshl_add_u32 v2, v170, 7, v196
	v_lshl_add_u32 v3, v171, 7, v196
	global_load_dwordx4 v[66:69], v2, s[24:25]
	global_load_dwordx4 v[58:61], v3, s[24:25]
	v_lshl_add_u32 v2, v172, 7, v196
	v_lshl_add_u32 v3, v173, 7, v196
	global_load_dwordx4 v[50:53], v2, s[24:25]
	global_load_dwordx4 v[42:45], v3, s[24:25]
	v_lshl_add_u32 v2, v166, 7, v196
	v_lshl_add_u32 v3, v167, 7, v196
	global_load_dwordx4 v[38:41], v2, s[24:25]
	global_load_dwordx4 v[30:33], v3, s[24:25]
	v_lshl_add_u32 v2, v168, 7, v196
	v_lshl_add_u32 v3, v169, 7, v196
	global_load_dwordx4 v[22:25], v2, s[24:25]
	global_load_dwordx4 v[18:21], v3, s[24:25]
	v_lshl_add_u32 v2, v162, 7, v196
	v_lshl_add_u32 v3, v163, 7, v196
	global_load_dwordx4 v[14:17], v2, s[24:25]
	global_load_dwordx4 v[10:13], v3, s[24:25]
	v_lshl_add_u32 v2, v164, 7, v196
	v_lshl_add_u32 v3, v165, 7, v196
	global_load_dwordx4 v[6:9], v2, s[24:25]
	s_nop 0
	global_load_dwordx4 v[2:5], v3, s[24:25]
	s_waitcnt vmcnt(39)
	v_perm_b32 v162, v159, v158, s41
	v_perm_b32 v158, v159, v158, s42
	v_perm_b32 v159, v161, v160, s41
	v_perm_b32 v160, v161, v160, s42
	v_perm_b32 v161, v155, v154, s41
	v_perm_b32 v154, v155, v154, s42
	v_perm_b32 v155, v157, v156, s41
	v_perm_b32 v156, v157, v156, s42
	s_waitcnt vmcnt(38)
	v_dot8_i32_i4 v157, v150, v162, 0
	v_readlane_b32 s36, v195, s46
	v_dot8c_i32_i4_e32 v157, v151, v159
	v_dot8c_i32_i4_e32 v157, v152, v161
	v_dot8c_i32_i4_e32 v157, v153, v155
	s_nop 2
	v_lshlrev_b32_e32 v157, 4, v157
	v_dot8c_i32_i4_e32 v157, v150, v158
	v_dot8c_i32_i4_e32 v157, v151, v160
	s_waitcnt vmcnt(37)
	v_dot8_i32_i4 v151, v146, v162, 0
	v_dot8c_i32_i4_e32 v157, v152, v154
	v_dot8c_i32_i4_e32 v151, v147, v159
	v_dot8c_i32_i4_e32 v151, v148, v161
	v_dot8c_i32_i4_e32 v151, v149, v155
	v_dot8c_i32_i4_e32 v157, v153, v156
	s_nop 1
	v_lshlrev_b32_e32 v151, 4, v151
	v_dot8c_i32_i4_e32 v151, v146, v158
	v_dot8c_i32_i4_e32 v151, v147, v160
	s_waitcnt vmcnt(36)
	v_dot8_i32_i4 v147, v142, v162, 0
	v_dot8c_i32_i4_e32 v151, v148, v154
	v_dot8c_i32_i4_e32 v147, v143, v159
	v_dot8c_i32_i4_e32 v147, v144, v161
	v_dot8c_i32_i4_e32 v147, v145, v155
	v_dot8c_i32_i4_e32 v151, v149, v156
	v_add_u32_dpp v150, v157, v157 quad_perm:[1,0,3,2] row_mask:0xf bank_mask:0xf bound_ctrl:1
	s_nop 0
	v_lshlrev_b32_e32 v147, 4, v147
	v_dot8c_i32_i4_e32 v147, v142, v158
	v_dot8c_i32_i4_e32 v147, v143, v160
	s_waitcnt vmcnt(35)
	v_dot8_i32_i4 v143, v138, v162, 0
	v_dot8c_i32_i4_e32 v147, v144, v154
	v_dot8c_i32_i4_e32 v143, v139, v159
	v_dot8c_i32_i4_e32 v143, v140, v161
	v_dot8c_i32_i4_e32 v143, v141, v155
	v_add_u32_dpp v146, v151, v151 quad_perm:[1,0,3,2] row_mask:0xf bank_mask:0xf bound_ctrl:1
	v_dot8c_i32_i4_e32 v147, v145, v156
	v_add_u32_dpp v150, v150, v150 quad_perm:[2,3,0,1] row_mask:0xf bank_mask:0xf bound_ctrl:1
	v_lshlrev_b32_e32 v143, 4, v143
	v_dot8c_i32_i4_e32 v143, v138, v158
	v_dot8c_i32_i4_e32 v143, v139, v160
	s_waitcnt vmcnt(34)
	v_dot8_i32_i4 v139, v134, v162, 0
	v_dot8c_i32_i4_e32 v143, v140, v154
	v_dot8c_i32_i4_e32 v139, v135, v159
	v_dot8c_i32_i4_e32 v139, v136, v161
	v_dot8c_i32_i4_e32 v139, v137, v155
	v_dot8c_i32_i4_e32 v143, v141, v156
	v_add_u32_dpp v146, v146, v146 quad_perm:[2,3,0,1] row_mask:0xf bank_mask:0xf bound_ctrl:1
	v_add_u32_dpp v142, v147, v147 quad_perm:[1,0,3,2] row_mask:0xf bank_mask:0xf bound_ctrl:1
	v_lshlrev_b32_e32 v139, 4, v139
	v_dot8c_i32_i4_e32 v139, v134, v158
	v_dot8c_i32_i4_e32 v139, v135, v160
	s_waitcnt vmcnt(33)
	v_dot8_i32_i4 v135, v130, v162, 0
	v_dot8c_i32_i4_e32 v139, v136, v154
	v_dot8c_i32_i4_e32 v135, v131, v159
	v_dot8c_i32_i4_e32 v135, v132, v161
	v_dot8c_i32_i4_e32 v135, v133, v155
	v_add_u32_dpp v138, v143, v143 quad_perm:[1,0,3,2] row_mask:0xf bank_mask:0xf bound_ctrl:1
	v_dot8c_i32_i4_e32 v139, v137, v156
	v_add_u32_dpp v150, v150, v150 row_half_mirror row_mask:0xf bank_mask:0xf bound_ctrl:1
	v_lshlrev_b32_e32 v135, 4, v135
	v_dot8c_i32_i4_e32 v135, v130, v158
	v_dot8c_i32_i4_e32 v135, v131, v160
	s_waitcnt vmcnt(32)
	v_dot8_i32_i4 v131, v126, v162, 0
	v_dot8c_i32_i4_e32 v135, v132, v154
	v_dot8c_i32_i4_e32 v131, v127, v159
	v_dot8c_i32_i4_e32 v131, v128, v161
	v_dot8c_i32_i4_e32 v131, v129, v155
	v_dot8c_i32_i4_e32 v135, v133, v156
	v_add_u32_dpp v146, v146, v146 row_half_mirror row_mask:0xf bank_mask:0xf bound_ctrl:1
	v_add_u32_dpp v142, v142, v142 quad_perm:[2,3,0,1] row_mask:0xf bank_mask:0xf bound_ctrl:1
	v_lshlrev_b32_e32 v131, 4, v131
	v_dot8c_i32_i4_e32 v131, v126, v158
	v_dot8c_i32_i4_e32 v131, v127, v160
	s_waitcnt vmcnt(31)
	v_dot8_i32_i4 v127, v110, v162, 0
	v_dot8c_i32_i4_e32 v131, v128, v154
	v_dot8c_i32_i4_e32 v127, v111, v159
	v_dot8c_i32_i4_e32 v127, v112, v161
	v_dot8c_i32_i4_e32 v127, v113, v155
	v_add_u32_dpp v138, v138, v138 quad_perm:[2,3,0,1] row_mask:0xf bank_mask:0xf bound_ctrl:1
	v_add_u32_dpp v134, v139, v139 quad_perm:[1,0,3,2] row_mask:0xf bank_mask:0xf bound_ctrl:1
	v_add_u32_dpp v130, v135, v135 quad_perm:[1,0,3,2] row_mask:0xf bank_mask:0xf bound_ctrl:1
	v_lshlrev_b32_e32 v127, 4, v127
	v_dot8c_i32_i4_e32 v127, v110, v158
	v_dot8c_i32_i4_e32 v127, v111, v160
	s_waitcnt vmcnt(30)
	v_dot8_i32_i4 v111, v98, v162, 0
	v_dot8c_i32_i4_e32 v127, v112, v154
	v_dot8c_i32_i4_e32 v111, v99, v159
	v_dot8c_i32_i4_e32 v111, v100, v161
	v_dot8c_i32_i4_e32 v111, v101, v155
	v_dot8c_i32_i4_e32 v131, v129, v156
	v_dot8c_i32_i4_e32 v127, v113, v156
	v_cndmask_b32_e64 v150, 0, v150, s[4:5]
	v_lshlrev_b32_e32 v111, 4, v111
	v_dot8c_i32_i4_e32 v111, v98, v158
	v_dot8c_i32_i4_e32 v111, v99, v160
	s_waitcnt vmcnt(29)
	v_dot8_i32_i4 v99, v78, v162, 0
	v_dot8c_i32_i4_e32 v111, v100, v154
	v_dot8c_i32_i4_e32 v99, v79, v159
	v_dot8c_i32_i4_e32 v99, v80, v161
	v_dot8c_i32_i4_e32 v99, v81, v155
	v_cndmask_b32_e64 v146, 0, v146, s[4:5]
	v_add_u32_dpp v142, v142, v142 row_half_mirror row_mask:0xf bank_mask:0xf bound_ctrl:1
	v_add_u32_dpp v138, v138, v138 row_half_mirror row_mask:0xf bank_mask:0xf bound_ctrl:1
	v_lshlrev_b32_e32 v99, 4, v99
	v_dot8c_i32_i4_e32 v99, v78, v158
	v_dot8c_i32_i4_e32 v99, v79, v160
	s_waitcnt vmcnt(28)
	v_dot8_i32_i4 v79, v70, v162, 0
	v_dot8c_i32_i4_e32 v99, v80, v154
	v_dot8c_i32_i4_e32 v79, v71, v159
	v_dot8c_i32_i4_e32 v79, v72, v161
	v_dot8c_i32_i4_e32 v79, v73, v155
	v_add_u32_dpp v134, v134, v134 quad_perm:[2,3,0,1] row_mask:0xf bank_mask:0xf bound_ctrl:1
	v_add_u32_dpp v130, v130, v130 quad_perm:[2,3,0,1] row_mask:0xf bank_mask:0xf bound_ctrl:1
	v_add_u32_dpp v126, v131, v131 quad_perm:[1,0,3,2] row_mask:0xf bank_mask:0xf bound_ctrl:1
	v_lshlrev_b32_e32 v79, 4, v79
	v_dot8c_i32_i4_e32 v79, v70, v158
	v_dot8c_i32_i4_e32 v79, v71, v160
	s_waitcnt vmcnt(27)
	v_dot8_i32_i4 v71, v62, v162, 0
	v_add_u32_dpp v110, v127, v127 quad_perm:[1,0,3,2] row_mask:0xf bank_mask:0xf bound_ctrl:1
	v_dot8c_i32_i4_e32 v71, v63, v159
	v_dot8c_i32_i4_e32 v71, v64, v161
	v_dot8c_i32_i4_e32 v71, v65, v155
	v_dot8c_i32_i4_e32 v111, v101, v156
	v_dot8c_i32_i4_e32 v99, v81, v156
	v_dot8c_i32_i4_e32 v79, v72, v154
	v_lshlrev_b32_e32 v71, 4, v71
	v_dot8c_i32_i4_e32 v71, v62, v158
	v_dot8c_i32_i4_e32 v71, v63, v160
	s_waitcnt vmcnt(26)
	v_dot8_i32_i4 v63, v54, v162, 0
	v_dot8c_i32_i4_e32 v71, v64, v154
	v_dot8c_i32_i4_e32 v63, v55, v159
	v_dot8c_i32_i4_e32 v63, v56, v161
	v_dot8c_i32_i4_e32 v63, v57, v155
	v_cndmask_b32_e64 v142, v150, v142, s[6:7]
	v_cndmask_b32_e64 v138, v146, v138, s[6:7]
	v_add_u32_dpp v134, v134, v134 row_half_mirror row_mask:0xf bank_mask:0xf bound_ctrl:1
	v_lshlrev_b32_e32 v63, 4, v63
	v_dot8c_i32_i4_e32 v63, v54, v158
	v_dot8c_i32_i4_e32 v63, v55, v160
	s_waitcnt vmcnt(25)
	v_dot8_i32_i4 v55, v46, v162, 0
	v_add_u32_dpp v130, v130, v130 row_half_mirror row_mask:0xf bank_mask:0xf bound_ctrl:1
	v_dot8c_i32_i4_e32 v55, v47, v159
	v_dot8c_i32_i4_e32 v55, v48, v161
	v_dot8c_i32_i4_e32 v55, v49, v155
	v_add_u32_dpp v126, v126, v126 quad_perm:[2,3,0,1] row_mask:0xf bank_mask:0xf bound_ctrl:1
	v_add_u32_dpp v110, v110, v110 quad_perm:[2,3,0,1] row_mask:0xf bank_mask:0xf bound_ctrl:1
	v_add_u32_dpp v98, v111, v111 quad_perm:[1,0,3,2] row_mask:0xf bank_mask:0xf bound_ctrl:1
	v_lshlrev_b32_e32 v55, 4, v55
	v_dot8c_i32_i4_e32 v55, v46, v158
	v_dot8c_i32_i4_e32 v55, v47, v160
	s_waitcnt vmcnt(24)
	v_dot8_i32_i4 v47, v34, v162, 0
	v_add_u32_dpp v78, v99, v99 quad_perm:[1,0,3,2] row_mask:0xf bank_mask:0xf bound_ctrl:1
	v_dot8c_i32_i4_e32 v47, v35, v159
	v_dot8c_i32_i4_e32 v47, v36, v161
	v_dot8c_i32_i4_e32 v47, v37, v155
	v_dot8c_i32_i4_e32 v79, v73, v156
	v_dot8c_i32_i4_e32 v71, v65, v156
	v_dot8c_i32_i4_e32 v63, v56, v154
	v_lshlrev_b32_e32 v47, 4, v47
	v_dot8c_i32_i4_e32 v47, v34, v158
	v_dot8c_i32_i4_e32 v47, v35, v160
	s_waitcnt vmcnt(23)
	v_dot8_i32_i4 v35, v26, v162, 0
	v_dot8c_i32_i4_e32 v55, v48, v154
	v_dot8c_i32_i4_e32 v35, v27, v159
	v_dot8c_i32_i4_e32 v35, v28, v161
	v_dot8c_i32_i4_e32 v35, v29, v155
	v_cndmask_b32_e64 v134, v142, v134, s[8:9]
	v_cndmask_b32_e64 v130, v138, v130, s[8:9]
	v_add_u32_dpp v126, v126, v126 row_half_mirror row_mask:0xf bank_mask:0xf bound_ctrl:1
	v_lshlrev_b32_e32 v35, 4, v35
	v_dot8c_i32_i4_e32 v35, v26, v158
	v_dot8c_i32_i4_e32 v35, v27, v160
	v_add_u32_dpp v110, v110, v110 row_half_mirror row_mask:0xf bank_mask:0xf bound_ctrl:1
	v_add_u32_dpp v98, v98, v98 quad_perm:[2,3,0,1] row_mask:0xf bank_mask:0xf bound_ctrl:1
	v_add_u32_dpp v78, v78, v78 quad_perm:[2,3,0,1] row_mask:0xf bank_mask:0xf bound_ctrl:1
	v_add_u32_dpp v70, v79, v79 quad_perm:[1,0,3,2] row_mask:0xf bank_mask:0xf bound_ctrl:1
	v_add_u32_dpp v62, v71, v71 quad_perm:[1,0,3,2] row_mask:0xf bank_mask:0xf bound_ctrl:1
	v_dot8c_i32_i4_e32 v63, v57, v156
	v_dot8c_i32_i4_e32 v55, v49, v156
	v_dot8c_i32_i4_e32 v47, v36, v154
	v_dot8c_i32_i4_e32 v35, v28, v154
	v_cndmask_b32_e64 v126, v134, v126, s[10:11]
	v_cndmask_b32_e64 v110, v130, v110, s[10:11]
	v_add_u32_dpp v98, v98, v98 row_half_mirror row_mask:0xf bank_mask:0xf bound_ctrl:1
	v_add_u32_dpp v78, v78, v78 row_half_mirror row_mask:0xf bank_mask:0xf bound_ctrl:1
	v_add_u32_dpp v70, v70, v70 quad_perm:[2,3,0,1] row_mask:0xf bank_mask:0xf bound_ctrl:1
	v_add_u32_dpp v62, v62, v62 quad_perm:[2,3,0,1] row_mask:0xf bank_mask:0xf bound_ctrl:1
	v_add_u32_dpp v54, v63, v63 quad_perm:[1,0,3,2] row_mask:0xf bank_mask:0xf bound_ctrl:1
	v_add_u32_dpp v46, v55, v55 quad_perm:[1,0,3,2] row_mask:0xf bank_mask:0xf bound_ctrl:1
	v_dot8c_i32_i4_e32 v47, v37, v156
	v_dot8c_i32_i4_e32 v35, v29, v156
	v_cndmask_b32_e64 v98, v126, v98, s[12:13]
	v_cndmask_b32_e64 v78, v110, v78, s[12:13]
	v_add_u32_dpp v70, v70, v70 row_half_mirror row_mask:0xf bank_mask:0xf bound_ctrl:1
	v_add_u32_dpp v62, v62, v62 row_half_mirror row_mask:0xf bank_mask:0xf bound_ctrl:1
	v_add_u32_dpp v54, v54, v54 quad_perm:[2,3,0,1] row_mask:0xf bank_mask:0xf bound_ctrl:1
	v_add_u32_dpp v46, v46, v46 quad_perm:[2,3,0,1] row_mask:0xf bank_mask:0xf bound_ctrl:1
	v_add_u32_dpp v34, v47, v47 quad_perm:[1,0,3,2] row_mask:0xf bank_mask:0xf bound_ctrl:1
	v_add_u32_dpp v26, v35, v35 quad_perm:[1,0,3,2] row_mask:0xf bank_mask:0xf bound_ctrl:1
	v_cndmask_b32_e64 v70, v98, v70, s[14:15]
	v_cndmask_b32_e64 v62, v78, v62, s[14:15]
	v_add_u32_dpp v54, v54, v54 row_half_mirror row_mask:0xf bank_mask:0xf bound_ctrl:1
	v_add_u32_dpp v46, v46, v46 row_half_mirror row_mask:0xf bank_mask:0xf bound_ctrl:1
	v_add_u32_dpp v34, v34, v34 quad_perm:[2,3,0,1] row_mask:0xf bank_mask:0xf bound_ctrl:1
	v_add_u32_dpp v26, v26, v26 quad_perm:[2,3,0,1] row_mask:0xf bank_mask:0xf bound_ctrl:1
	v_cndmask_b32_e64 v54, v70, v54, s[16:17]
	v_cndmask_b32_e64 v46, v62, v46, s[16:17]
	v_add_u32_dpp v34, v34, v34 row_half_mirror row_mask:0xf bank_mask:0xf bound_ctrl:1
	v_add_u32_dpp v26, v26, v26 row_half_mirror row_mask:0xf bank_mask:0xf bound_ctrl:1
	v_cndmask_b32_e64 v34, v54, v34, s[18:19]
	v_cndmask_b32_e64 v26, v46, v26, s[18:19]
	v_cvt_f32_i32_e32 v27, v34
	v_cvt_f32_i32_e32 v26, v26
	v_mul_f32_e32 v27, s36, v27
	v_mul_f32_e32 v26, s36, v26
	v_cvt_pk_f16_f32 v28, v27, v26
	v_lshl_add_u64 v[26:27], v[182:183], 0, s[34:35]
	global_store_dword v[26:27], v28, off
	v_lshl_add_u64 v[188:189], v[188:189], 0, s[28:29]
	s_mov_b32 s47, s31
	s_cbranch_scc0 .LBB0_3962
	s_mov_b64 s[34:35], 0
